# w_o / mlp2 residual epilogue stage 1: the four gate-row loads of each block issued together, counted waits 3/2/1/0 (4 blocks); on top of v113
# baseline (speedup 1.0000x reference)
.LBB0_1506:
	s_add_i32 s5, s65, -16
	s_ashr_i32 s5, s5, 3
	s_add_i32 s5, s5, 1
	s_cmp_gt_i32 s65, 15
	s_cselect_b32 s5, s5, 0
	s_add_i32 s5, s5, s3
	s_mul_hi_i32 s18, s5, 0x6000
	s_mulk_i32 s5, 0x6000
	s_add_u32 s5, s14, s5
	s_addc_u32 s20, s15, s18
	s_lshl_b32 s18, s66, 8
	s_ashr_i32 s19, s18, 31
	v_and_b32_e32 v128, 63, v136
	v_bfe_u32 v130, v136, 4, 2
	s_lshl_b64 s[24:25], s[18:19], 2
	s_barrier
	s_add_u32 s26, s5, s24
	v_lshl_add_u32 v138, v130, 2, s59
	s_addc_u32 s27, s20, s25
	v_ashrrev_i32_e32 v139, 31, v138
	v_lshl_add_u64 v[134:135], v[138:139], 2, s[26:27]
	s_movk_i32 s5, 0x2000
	v_lshl_add_u64 v[130:131], v[134:135], 0, s[12:13]
	v_add_co_u32_e32 v134, vcc, s5, v134
	v_add_u32_e32 v142, s57, v137
	s_nop 0
	v_addc_co_u32_e32 v135, vcc, 0, v135, vcc
	global_load_dwordx4 v[134:137], v[134:135], off
	global_load_dwordx4 v[144:147], v[130:131], off offset:64
	global_load_dwordx4 v[148:151], v[130:131], off offset:512
	global_load_dwordx4 v[152:155], v[130:131], off offset:576
	s_movk_i32 s5, 0x410
	v_lshl_add_u32 v143, v138, 2, 0
	s_lshl_b32 s22, s4, 4
	s_lshl_b32 s20, s65, 8
	s_ashr_i32 s23, s22, 31
	s_ashr_i32 s21, s20, 31
	s_lshl_b64 s[26:27], s[22:23], 12
	v_lshlrev_b32_e32 v132, 2, v128
	s_add_u32 s16, s16, s26
	v_ashrrev_i32_e32 v133, 31, v132
	s_addc_u32 s17, s17, s27
	s_mulk_i32 s4, 0x4100
	v_readlane_b32 s58, v254, 49
	v_readlane_b32 s60, v254, 51
	v_readlane_b32 s56, v254, 53
	v_readlane_b32 s59, v254, 50
	v_readlane_b32 s61, v254, 52
	v_readlane_b32 s57, v254, 54
	s_waitcnt vmcnt(3)
	v_pk_mul_f32 v[138:139], v[124:125], v[134:135]
	v_mul_lo_u32 v124, v142, s5
	v_add_u32_e32 v124, v143, v124
	v_pk_mul_f32 v[114:115], v[114:115], v[136:137]
	v_pk_mul_f32 v[112:113], v[112:113], v[134:135]
	ds_write_b128 v124, v[112:115] offset:49920
	v_pk_mul_f32 v[140:141], v[126:127], v[136:137]
	v_pk_mul_f32 v[122:123], v[122:123], v[136:137]
	v_pk_mul_f32 v[120:121], v[120:121], v[134:135]
	v_pk_mul_f32 v[118:119], v[118:119], v[136:137]
	v_pk_mul_f32 v[116:117], v[116:117], v[134:135]
	ds_write_b128 v124, v[138:141]
	ds_write_b128 v124, v[120:123] offset:16640
	ds_write_b128 v124, v[116:119] offset:33280
	s_waitcnt vmcnt(2)
	v_pk_mul_f32 v[98:99], v[98:99], v[146:147]
	v_pk_mul_f32 v[96:97], v[96:97], v[144:145]
	ds_write_b128 v124, v[96:99] offset:49984
	v_pk_mul_f32 v[110:111], v[110:111], v[146:147]
	v_pk_mul_f32 v[108:109], v[108:109], v[144:145]
	v_pk_mul_f32 v[106:107], v[106:107], v[146:147]
	v_pk_mul_f32 v[104:105], v[104:105], v[144:145]
	v_pk_mul_f32 v[102:103], v[102:103], v[146:147]
	v_pk_mul_f32 v[100:101], v[100:101], v[144:145]
	ds_write_b128 v124, v[108:111] offset:64
	ds_write_b128 v124, v[104:107] offset:16704
	ds_write_b128 v124, v[100:103] offset:33344
	s_waitcnt vmcnt(1)
	v_pk_mul_f32 v[82:83], v[82:83], v[150:151]
	v_pk_mul_f32 v[80:81], v[80:81], v[148:149]
	ds_write_b128 v124, v[80:83] offset:50432
	v_pk_mul_f32 v[94:95], v[94:95], v[150:151]
	v_pk_mul_f32 v[92:93], v[92:93], v[148:149]
	v_pk_mul_f32 v[90:91], v[90:91], v[150:151]
	v_pk_mul_f32 v[88:89], v[88:89], v[148:149]
	v_pk_mul_f32 v[86:87], v[86:87], v[150:151]
	v_pk_mul_f32 v[84:85], v[84:85], v[148:149]
	ds_write_b128 v124, v[92:95] offset:512
	ds_write_b128 v124, v[88:91] offset:17152
	ds_write_b128 v124, v[84:87] offset:33792
	s_waitcnt vmcnt(0)
	v_pk_mul_f32 v[66:67], v[66:67], v[154:155]
	v_pk_mul_f32 v[64:65], v[64:65], v[152:153]
	ds_write_b128 v124, v[64:67] offset:50496
	v_lshl_add_u64 v[64:65], v[132:133], 2, s[16:17]
	s_lshl_b64 s[16:17], s[20:21], 12
	s_add_u32 s16, s16, s24
	v_pk_mul_f32 v[78:79], v[78:79], v[154:155]
	v_pk_mul_f32 v[76:77], v[76:77], v[152:153]
	s_addc_u32 s17, s17, s25
	s_add_i32 s4, s4, 0
	ds_write_b128 v124, v[76:79] offset:576
	v_lshl_add_u32 v76, v128, 4, s4
	v_readlane_b32 s4, v254, 24
	v_pk_mul_f32 v[70:71], v[70:71], v[154:155]
	v_pk_mul_f32 v[68:69], v[68:69], v[152:153]
	s_add_u32 s4, s14, s4
	ds_write_b128 v124, v[68:71] offset:33856
	v_lshl_add_u64 v[68:69], v[64:65], 0, s[16:17]
	s_addc_u32 s5, s15, 0
	s_lshl_b64 s[16:17], s[22:23], 11
	v_pk_mul_f32 v[74:75], v[74:75], v[154:155]
	v_pk_mul_f32 v[72:73], v[72:73], v[152:153]
	v_lshl_add_u64 v[70:71], v[132:133], 1, s[16:17]
	ds_write_b128 v124, v[72:75] offset:17216
	v_lshl_add_u64 v[64:65], s[4:5], 0, v[70:71]
	s_lshl_b64 s[4:5], s[20:21], 11
	s_lshl_b64 s[16:17], s[18:19], 1
	s_waitcnt lgkmcnt(0)
	s_barrier
	s_add_u32 s16, s4, s16
	s_addc_u32 s17, s5, s17
	v_lshl_add_u64 v[72:73], v[64:65], 0, s[16:17]
	s_mov_b64 s[18:19], 0
	v_mov_b32_e32 v77, v76
	s_branch .LBB0_1508

.LBB0_1524:
	s_waitcnt lgkmcnt(0)
	s_barrier
	s_waitcnt lgkmcnt(0)
	global_load_dwordx4 v[64:67], v[130:131], off
	global_load_dwordx4 v[144:147], v[130:131], off offset:64
	global_load_dwordx4 v[148:151], v[130:131], off offset:512
	global_load_dwordx4 v[152:155], v[130:131], off offset:576
	v_readlane_b32 s4, v254, 25
	s_add_u32 s14, s14, s4
	s_addc_u32 s15, s15, 0
	s_waitcnt vmcnt(3)
	v_pk_mul_f32 v[50:51], v[50:51], v[66:67]
	v_pk_mul_f32 v[48:49], v[48:49], v[64:65]
	ds_write_b128 v124, v[48:51] offset:49920
	v_pk_mul_f32 v[62:63], v[62:63], v[66:67]
	v_pk_mul_f32 v[60:61], v[60:61], v[64:65]
	v_pk_mul_f32 v[58:59], v[58:59], v[66:67]
	v_pk_mul_f32 v[56:57], v[56:57], v[64:65]
	v_pk_mul_f32 v[54:55], v[54:55], v[66:67]
	v_pk_mul_f32 v[52:53], v[52:53], v[64:65]
	ds_write_b128 v124, v[60:63]
	ds_write_b128 v124, v[56:59] offset:16640
	ds_write_b128 v124, v[52:55] offset:33280
	s_waitcnt vmcnt(2)
	v_pk_mul_f32 v[34:35], v[34:35], v[146:147]
	v_pk_mul_f32 v[32:33], v[32:33], v[144:145]
	ds_write_b128 v124, v[32:35] offset:49984
	v_pk_mul_f32 v[46:47], v[46:47], v[146:147]
	v_pk_mul_f32 v[44:45], v[44:45], v[144:145]
	v_pk_mul_f32 v[42:43], v[42:43], v[146:147]
	v_pk_mul_f32 v[40:41], v[40:41], v[144:145]
	v_pk_mul_f32 v[38:39], v[38:39], v[146:147]
	v_pk_mul_f32 v[36:37], v[36:37], v[144:145]
	ds_write_b128 v124, v[44:47] offset:64
	ds_write_b128 v124, v[40:43] offset:16704
	ds_write_b128 v124, v[36:39] offset:33344
	s_waitcnt vmcnt(1)
	v_pk_mul_f32 v[18:19], v[18:19], v[150:151]
	v_pk_mul_f32 v[16:17], v[16:17], v[148:149]
	ds_write_b128 v124, v[16:19] offset:50432
	v_pk_mul_f32 v[30:31], v[30:31], v[150:151]
	v_pk_mul_f32 v[28:29], v[28:29], v[148:149]
	v_pk_mul_f32 v[26:27], v[26:27], v[150:151]
	v_pk_mul_f32 v[24:25], v[24:25], v[148:149]
	v_pk_mul_f32 v[22:23], v[22:23], v[150:151]
	v_pk_mul_f32 v[20:21], v[20:21], v[148:149]
	ds_write_b128 v124, v[28:31] offset:512
	ds_write_b128 v124, v[24:27] offset:17152
	ds_write_b128 v124, v[20:23] offset:33792
	s_waitcnt vmcnt(0)
	v_pk_mul_f32 v[14:15], v[14:15], v[154:155]
	v_pk_mul_f32 v[12:13], v[12:13], v[152:153]
	v_pk_mul_f32 v[10:11], v[10:11], v[154:155]
	v_pk_mul_f32 v[8:9], v[8:9], v[152:153]
	v_pk_mul_f32 v[6:7], v[6:7], v[154:155]
	v_pk_mul_f32 v[4:5], v[4:5], v[152:153]
	v_pk_mul_f32 v[2:3], v[2:3], v[154:155]
	v_pk_mul_f32 v[0:1], v[0:1], v[152:153]
	ds_write_b128 v124, v[12:15] offset:576
	ds_write_b128 v124, v[8:11] offset:17216
	ds_write_b128 v124, v[4:7] offset:33856
	ds_write_b128 v124, v[0:3] offset:50496
	s_waitcnt lgkmcnt(0)
	s_barrier
	v_lshl_add_u64 v[0:1], s[14:15], 0, v[70:71]
	v_lshl_add_u64 v[4:5], v[0:1], 0, s[16:17]
	s_mov_b64 s[14:15], 0
	s_branch .LBB0_1526

.LBB0_1864:
	s_add_i32 s5, s63, -16
	s_ashr_i32 s5, s5, 3
	s_add_i32 s5, s5, 1
	s_cmp_gt_i32 s63, 15
	s_cselect_b32 s5, s5, 0
	s_add_i32 s3, s5, s3
	s_mul_hi_i32 s5, s3, 0x6000
	s_mulk_i32 s3, 0x6000
	s_add_u32 s3, s14, s3
	s_addc_u32 s5, s15, s5
	s_lshl_b32 s18, s64, 8
	s_ashr_i32 s19, s18, 31
	v_and_b32_e32 v128, 63, v136
	v_bfe_u32 v130, v136, 4, 2
	s_lshl_b64 s[24:25], s[18:19], 2
	s_barrier
	s_add_u32 s26, s3, s24
	v_lshl_add_u32 v138, v130, 2, s57
	s_addc_u32 s27, s5, s25
	v_ashrrev_i32_e32 v139, 31, v138
	v_lshl_add_u64 v[134:135], v[138:139], 2, s[26:27]
	s_mov_b64 s[26:27], 0x5000
	s_movk_i32 s3, 0x5000
	v_lshl_add_u64 v[130:131], v[134:135], 0, s[26:27]
	v_add_co_u32_e32 v134, vcc, s3, v134
	v_add_u32_e32 v142, s55, v137
	s_nop 0
	v_addc_co_u32_e32 v135, vcc, 0, v135, vcc
	global_load_dwordx4 v[134:137], v[134:135], off
	global_load_dwordx4 v[144:147], v[130:131], off offset:64
	global_load_dwordx4 v[148:151], v[130:131], off offset:512
	global_load_dwordx4 v[152:155], v[130:131], off offset:576
	s_movk_i32 s3, 0x410
	v_lshl_add_u32 v143, v138, 2, 0
	s_lshl_b32 s22, s4, 4
	s_lshl_b32 s20, s63, 8
	s_ashr_i32 s23, s22, 31
	s_ashr_i32 s21, s20, 31
	s_lshl_b64 s[26:27], s[22:23], 12
	v_lshlrev_b32_e32 v132, 2, v128
	s_add_u32 s16, s16, s26
	v_ashrrev_i32_e32 v133, 31, v132
	s_addc_u32 s17, s17, s27
	s_mulk_i32 s4, 0x4100
	v_readlane_b32 s58, v254, 49
	v_readlane_b32 s60, v254, 51
	v_readlane_b32 s56, v254, 53
	v_readlane_b32 s59, v254, 50
	v_readlane_b32 s61, v254, 52
	v_readlane_b32 s57, v254, 54
	s_waitcnt vmcnt(3)
	v_pk_mul_f32 v[138:139], v[124:125], v[134:135]
	v_mul_lo_u32 v124, v142, s3
	v_add_u32_e32 v124, v143, v124
	v_pk_mul_f32 v[114:115], v[114:115], v[136:137]
	v_pk_mul_f32 v[112:113], v[112:113], v[134:135]
	ds_write_b128 v124, v[112:115] offset:49920
	v_pk_mul_f32 v[140:141], v[126:127], v[136:137]
	v_pk_mul_f32 v[122:123], v[122:123], v[136:137]
	v_pk_mul_f32 v[120:121], v[120:121], v[134:135]
	v_pk_mul_f32 v[118:119], v[118:119], v[136:137]
	v_pk_mul_f32 v[116:117], v[116:117], v[134:135]
	ds_write_b128 v124, v[138:141]
	ds_write_b128 v124, v[120:123] offset:16640
	ds_write_b128 v124, v[116:119] offset:33280
	s_waitcnt vmcnt(2)
	v_pk_mul_f32 v[98:99], v[98:99], v[146:147]
	v_pk_mul_f32 v[96:97], v[96:97], v[144:145]
	ds_write_b128 v124, v[96:99] offset:49984
	v_pk_mul_f32 v[110:111], v[110:111], v[146:147]
	v_pk_mul_f32 v[108:109], v[108:109], v[144:145]
	v_pk_mul_f32 v[106:107], v[106:107], v[146:147]
	v_pk_mul_f32 v[104:105], v[104:105], v[144:145]
	v_pk_mul_f32 v[102:103], v[102:103], v[146:147]
	v_pk_mul_f32 v[100:101], v[100:101], v[144:145]
	ds_write_b128 v124, v[108:111] offset:64
	ds_write_b128 v124, v[104:107] offset:16704
	ds_write_b128 v124, v[100:103] offset:33344
	s_waitcnt vmcnt(1)
	v_pk_mul_f32 v[82:83], v[82:83], v[150:151]
	v_pk_mul_f32 v[80:81], v[80:81], v[148:149]
	ds_write_b128 v124, v[80:83] offset:50432
	v_pk_mul_f32 v[94:95], v[94:95], v[150:151]
	v_pk_mul_f32 v[92:93], v[92:93], v[148:149]
	v_pk_mul_f32 v[90:91], v[90:91], v[150:151]
	v_pk_mul_f32 v[88:89], v[88:89], v[148:149]
	v_pk_mul_f32 v[86:87], v[86:87], v[150:151]
	v_pk_mul_f32 v[84:85], v[84:85], v[148:149]
	ds_write_b128 v124, v[92:95] offset:512
	ds_write_b128 v124, v[88:91] offset:17152
	ds_write_b128 v124, v[84:87] offset:33792
	s_waitcnt vmcnt(0)
	v_pk_mul_f32 v[66:67], v[66:67], v[154:155]
	v_pk_mul_f32 v[64:65], v[64:65], v[152:153]
	ds_write_b128 v124, v[64:67] offset:50496
	v_lshl_add_u64 v[64:65], v[132:133], 2, s[16:17]
	s_lshl_b64 s[16:17], s[20:21], 12
	s_add_u32 s16, s16, s24
	v_pk_mul_f32 v[78:79], v[78:79], v[154:155]
	v_pk_mul_f32 v[76:77], v[76:77], v[152:153]
	s_addc_u32 s17, s17, s25
	s_add_i32 s3, s4, 0
	ds_write_b128 v124, v[76:79] offset:576
	v_lshl_add_u32 v76, v128, 4, s3
	v_readlane_b32 s3, v254, 24
	v_pk_mul_f32 v[70:71], v[70:71], v[154:155]
	v_pk_mul_f32 v[68:69], v[68:69], v[152:153]
	s_add_u32 s4, s14, s3
	ds_write_b128 v124, v[68:71] offset:33856
	v_lshl_add_u64 v[68:69], v[64:65], 0, s[16:17]
	s_addc_u32 s5, s15, 0
	s_lshl_b64 s[16:17], s[22:23], 11
	v_pk_mul_f32 v[74:75], v[74:75], v[154:155]
	v_pk_mul_f32 v[72:73], v[72:73], v[152:153]
	v_lshl_add_u64 v[70:71], v[132:133], 1, s[16:17]
	ds_write_b128 v124, v[72:75] offset:17216
	v_lshl_add_u64 v[64:65], s[4:5], 0, v[70:71]
	s_lshl_b64 s[4:5], s[20:21], 11
	s_lshl_b64 s[16:17], s[18:19], 1
	s_waitcnt lgkmcnt(0)
	s_barrier
	s_add_u32 s16, s4, s16
	s_addc_u32 s17, s5, s17
	v_lshl_add_u64 v[72:73], v[64:65], 0, s[16:17]
	s_mov_b64 s[18:19], 0
	v_mov_b32_e32 v77, v76
	s_branch .LBB0_1866

.LBB0_1882:
	s_waitcnt lgkmcnt(0)
	s_barrier
	s_waitcnt lgkmcnt(0)
	global_load_dwordx4 v[64:67], v[130:131], off
	global_load_dwordx4 v[144:147], v[130:131], off offset:64
	global_load_dwordx4 v[148:151], v[130:131], off offset:512
	global_load_dwordx4 v[152:155], v[130:131], off offset:576
	v_readlane_b32 s3, v254, 25
	s_add_u32 s14, s14, s3
	s_addc_u32 s15, s15, 0
	s_waitcnt vmcnt(3)
	v_pk_mul_f32 v[50:51], v[50:51], v[66:67]
	v_pk_mul_f32 v[48:49], v[48:49], v[64:65]
	ds_write_b128 v124, v[48:51] offset:49920
	v_pk_mul_f32 v[62:63], v[62:63], v[66:67]
	v_pk_mul_f32 v[60:61], v[60:61], v[64:65]
	v_pk_mul_f32 v[58:59], v[58:59], v[66:67]
	v_pk_mul_f32 v[56:57], v[56:57], v[64:65]
	v_pk_mul_f32 v[54:55], v[54:55], v[66:67]
	v_pk_mul_f32 v[52:53], v[52:53], v[64:65]
	ds_write_b128 v124, v[60:63]
	ds_write_b128 v124, v[56:59] offset:16640
	ds_write_b128 v124, v[52:55] offset:33280
	s_waitcnt vmcnt(2)
	v_pk_mul_f32 v[34:35], v[34:35], v[146:147]
	v_pk_mul_f32 v[32:33], v[32:33], v[144:145]
	ds_write_b128 v124, v[32:35] offset:49984
	v_pk_mul_f32 v[46:47], v[46:47], v[146:147]
	v_pk_mul_f32 v[44:45], v[44:45], v[144:145]
	v_pk_mul_f32 v[42:43], v[42:43], v[146:147]
	v_pk_mul_f32 v[40:41], v[40:41], v[144:145]
	v_pk_mul_f32 v[38:39], v[38:39], v[146:147]
	v_pk_mul_f32 v[36:37], v[36:37], v[144:145]
	ds_write_b128 v124, v[44:47] offset:64
	ds_write_b128 v124, v[40:43] offset:16704
	ds_write_b128 v124, v[36:39] offset:33344
	s_waitcnt vmcnt(1)
	v_pk_mul_f32 v[18:19], v[18:19], v[150:151]
	v_pk_mul_f32 v[16:17], v[16:17], v[148:149]
	ds_write_b128 v124, v[16:19] offset:50432
	v_pk_mul_f32 v[30:31], v[30:31], v[150:151]
	v_pk_mul_f32 v[28:29], v[28:29], v[148:149]
	v_pk_mul_f32 v[26:27], v[26:27], v[150:151]
	v_pk_mul_f32 v[24:25], v[24:25], v[148:149]
	v_pk_mul_f32 v[22:23], v[22:23], v[150:151]
	v_pk_mul_f32 v[20:21], v[20:21], v[148:149]
	ds_write_b128 v124, v[28:31] offset:512
	ds_write_b128 v124, v[24:27] offset:17152
	ds_write_b128 v124, v[20:23] offset:33792
	s_waitcnt vmcnt(0)
	v_pk_mul_f32 v[14:15], v[14:15], v[154:155]
	v_pk_mul_f32 v[12:13], v[12:13], v[152:153]
	v_pk_mul_f32 v[10:11], v[10:11], v[154:155]
	v_pk_mul_f32 v[8:9], v[8:9], v[152:153]
	v_pk_mul_f32 v[6:7], v[6:7], v[154:155]
	v_pk_mul_f32 v[4:5], v[4:5], v[152:153]
	v_pk_mul_f32 v[2:3], v[2:3], v[154:155]
	v_pk_mul_f32 v[0:1], v[0:1], v[152:153]
	ds_write_b128 v124, v[12:15] offset:576
	ds_write_b128 v124, v[8:11] offset:17216
	ds_write_b128 v124, v[4:7] offset:33856
	ds_write_b128 v124, v[0:3] offset:50496
	s_waitcnt lgkmcnt(0)
	s_barrier
	v_lshl_add_u64 v[0:1], s[14:15], 0, v[70:71]
	v_lshl_add_u64 v[4:5], v[0:1], 0, s[16:17]
	s_mov_b64 s[14:15], 0
	s_branch .LBB0_1884
